# sample-attention loop slimming 2: key-norm table written by all lanes without exec masking, unscaled fp8 MFMA form (scales were 1.0), redundant scalar recompute dropped
# speedup vs baseline: 1.0088x; 1.0008x over previous
; #define LAS __attribute__((address_space(3)))
; DI void attn_sample_phase(const Args& a, LAS unsigned char* lds, int vcu, int G, int tid, int lane, int wave) {
;     ...
;             { const LAS unsigned char* c8b = C8 + (j & 1) * 8704; const LAS float* spe = SSPE + (j & 1) * 32;
; #pragma unroll
;                 for (int kb = 0; kb < 2; ++kb) { f32x4 acc[4] = {};
; #pragma unroll
;                     for (int ks = 0; ks < 2; ++ks) { const LAS unsigned char* ap = c8b + (kb * 16 + r16) * 272 + 128 * ks + 32 * q4;
;                         const u32x4 x0 = *(const LAS u32x4*)ap, x1 = *(const LAS u32x4*)(ap + 16);
;                         const v8i_t af = {(int)x0.x, (int)x0.y, (int)x0.z, (int)x0.w, (int)x1.x, (int)x1.y, (int)x1.z, (int)x1.w};
; #pragma unroll
;                         for (int nb = 0; nb < 4; ++nb) acc[nb] = __builtin_amdgcn_mfma_scale_f32_16x16x128_f8f6f4(af, wf8[nb][ks], acc[nb], 0, 0, 0, 0x7F7F7F7F, 0, 0x7F7F7F7F); }
;                     f32x4 sq = (acc[0] * acc[0] + acc[1] * acc[1] + acc[2] * acc[2] + acc[3] * acc[3]) * (1.f / 256.f);
;                     sq.x = row16_sum(sq.x); sq.y = row16_sum(sq.y); sq.z = row16_sum(sq.z); sq.w = row16_sum(sq.w);
;                     if (r16 == 0) { const f32x4 pe = *(const LAS f32x4*)(spe + kb * 16 + 4 * q4); f32x4 r;
;                         r.x = __builtin_amdgcn_rsqf((sq.x + pe.x) * (1.f / 96.f) + EPS); r.y = __builtin_amdgcn_rsqf((sq.y + pe.y) * (1.f / 96.f) + EPS);
;                         r.z = __builtin_amdgcn_rsqf((sq.z + pe.z) * (1.f / 96.f) + EPS); r.w = __builtin_amdgcn_rsqf((sq.w + pe.w) * (1.f / 96.f) + EPS);
;                         *(LAS f32x4*)(RI + wave * 32 + kb * 16 + 4 * q4) = r; } } }
.LBB0_904:
	s_and_b32 s8, s26, 1
	s_mul_i32 s9, s8, 0x2200
	v_add_u32_e32 v2, s9, v202
	s_lshl_b32 s8, s8, 7
	s_add_i32 s8, s8, 0x17a00
	v_lshl_add_u32 v254, v140, 2, s8
	ds_read_b128 v[212:215], v2 offset:56832
	ds_read_b128 v[216:219], v2 offset:56848
	ds_read_b128 v[236:239], v2 offset:56960
	ds_read_b128 v[240:243], v2 offset:56976
	ds_read_b128 v[246:249], v2 offset:61184
	ds_read_b128 v[250:253], v2 offset:61200
	ds_read_b32 v232, v254
	ds_read_b32 v233, v254 offset:64
	s_waitcnt lgkmcnt(6)
	v_mfma_f32_16x16x128_f8f6f4 v[220:223], v[36:43], v[212:219], 0
	v_mfma_f32_16x16x128_f8f6f4 v[136:139], v[20:27], v[212:219], 0
	v_mfma_f32_16x16x128_f8f6f4 v[224:227], v[52:59], v[212:219], 0
	v_mfma_f32_16x16x128_f8f6f4 v[228:231], v[68:75], v[212:219], 0
	s_waitcnt lgkmcnt(4)
	v_mfma_f32_16x16x128_f8f6f4 v[220:223], v[44:51], v[236:243], v[220:223]
	ds_read_b128 v[212:215], v2 offset:61312
	ds_read_b128 v[216:219], v2 offset:61328
	v_mfma_f32_16x16x128_f8f6f4 v[136:139], v[28:35], v[236:243], v[136:139]
	v_mfma_f32_16x16x128_f8f6f4 v[224:227], v[60:67], v[236:243], v[224:227]
	v_mfma_f32_16x16x128_f8f6f4 v[228:231], v[76:83], v[236:243], v[228:231]
	v_lshlrev_b32_e32 v255, 7, v158
	v_lshl_add_u32 v255, v140, 2, v255
	v_add_u32_e32 v255, 0x17600, v255
	s_nop 4
	v_mul_f32_e32 v234, v220, v220
	v_fmac_f32_e32 v234, v221, v221
	v_fmac_f32_e32 v234, v222, v222
	v_fmac_f32_e32 v234, v223, v223
	s_waitcnt lgkmcnt(4)
	v_mfma_f32_16x16x128_f8f6f4 v[220:223], v[36:43], v[246:253], 0
	v_fmac_f32_e32 v234, v136, v136
	v_fmac_f32_e32 v234, v137, v137
	v_fmac_f32_e32 v234, v138, v138
	v_fmac_f32_e32 v234, v139, v139
	v_mfma_f32_16x16x128_f8f6f4 v[136:139], v[68:75], v[246:253], 0
	v_fmac_f32_e32 v234, v224, v224
	v_fmac_f32_e32 v234, v225, v225
	v_fmac_f32_e32 v234, v226, v226
	v_fmac_f32_e32 v234, v227, v227
	v_mfma_f32_16x16x128_f8f6f4 v[224:227], v[20:27], v[246:253], 0
	v_fmac_f32_e32 v234, v228, v228
	v_fmac_f32_e32 v234, v229, v229
	v_fmac_f32_e32 v234, v230, v230
	v_fmac_f32_e32 v234, v231, v231
	v_mfma_f32_16x16x128_f8f6f4 v[228:231], v[52:59], v[246:253], 0
	s_waitcnt lgkmcnt(0)
	v_mov_b32_e32 v235, v234
	v_mfma_f32_16x16x128_f8f6f4 v[220:223], v[44:51], v[212:219], v[220:223]
	s_nop 0
	v_permlane32_swap_b32_e32 v235, v234
	v_add_f32_e32 v234, v234, v235
	v_mfma_f32_16x16x128_f8f6f4 v[136:139], v[76:83], v[212:219], v[136:139]
	v_mov_b32_e32 v235, v234
	s_nop 1
	v_permlane16_swap_b32_e32 v235, v234
	v_add_f32_e32 v234, v234, v235
	v_mfma_f32_16x16x128_f8f6f4 v[224:227], v[28:35], v[212:219], v[224:227]
	v_fmamk_f32 v234, v234, 0x3b800000, v232
	v_fmamk_f32 v234, v234, 0x3c2aaaab, v209
	v_rsq_f32_e32 v234, v234
	v_mfma_f32_16x16x128_f8f6f4 v[228:231], v[60:67], v[212:219], v[228:231]
	ds_write_b32 v255, v234
	v_mul_f32_e32 v234, v220, v220
	v_fmac_f32_e32 v234, v221, v221
	v_fmac_f32_e32 v234, v222, v222
	v_fmac_f32_e32 v234, v223, v223
	v_fmac_f32_e32 v234, v136, v136
	v_fmac_f32_e32 v234, v137, v137
	v_fmac_f32_e32 v234, v138, v138
	v_fmac_f32_e32 v234, v139, v139
	v_fmac_f32_e32 v234, v224, v224
	v_fmac_f32_e32 v234, v225, v225
	v_fmac_f32_e32 v234, v226, v226
	v_fmac_f32_e32 v234, v227, v227
	v_fmac_f32_e32 v234, v228, v228
	v_fmac_f32_e32 v234, v229, v229
	v_fmac_f32_e32 v234, v230, v230
	v_fmac_f32_e32 v234, v231, v231
	v_mov_b32_e32 v235, v234
	s_nop 1
	v_permlane32_swap_b32_e32 v235, v234
	v_add_f32_e32 v234, v234, v235
	v_mov_b32_e32 v235, v234
	s_nop 1
	v_permlane16_swap_b32_e32 v235, v234
	v_add_f32_e32 v234, v234, v235
	v_fmamk_f32 v234, v234, 0x3b800000, v233
	v_fmamk_f32 v234, v234, 0x3c2aaaab, v209
	v_rsq_f32_e32 v234, v234
	ds_write_b32 v255, v234 offset:64
